# gdn_prep scan-operand (OPS) stores nt
# speedup vs baseline: 1.0253x; 1.0253x over previous
; #define LAS __attribute__((address_space(3)))
; __device__ __forceinline__ void gdn_prep_all(const Params& P, LAS unsigned char* lds, int tid, int lane, int wave, int G) {
;     ...
;         {
;             const int i = lane & 15, q4 = lane >> 4;
; #pragma unroll
;             for (int ff = 0; ff < 2; ++ff) { const int fr = wq * 2 + ff, rho = fr >> 1, s2 = fr & 1, row = 16 * rho + i;
;                 const v2u lo = *(const LAS v2u*)(hb + XW_OFF + row * 144 + (32 * s2 + 4 * q4) * 2), hi = *(const LAS v2u*)(hb + XW_OFF + row * 144 + (32 * s2 + 16 + 4 * q4) * 2);
;                 v4u o; o.x = lo.x; o.y = lo.y; o.z = hi.x; o.w = hi.y;
;                 *(v4u*)(ops + OPS_W + (fr * 64 + lane) * 16) = o; }
;         }
;         __syncthreads();
;         par ^= 1;
.LBB0_346:
	v_add_u32_e32 v31, 0x6800, v179
	s_waitcnt lgkmcnt(0)
	s_barrier
	ds_read2_b64 v[32:35], v31 offset0:128 offset1:132
	v_lshl_add_u64 v[36:37], s[16:17], 0, v[98:99]
	s_xor_b32 s84, s84, 1
	s_andn2_b64 vcc, exec, s[90:91]
	s_waitcnt lgkmcnt(0)
	global_store_dwordx4 v[36:37], v[32:35], off nt
	ds_read2_b64 v[32:35], v31 offset0:136 offset1:140
	s_waitcnt lgkmcnt(0)
	global_store_dwordx4 v[36:37], v[32:35], off offset:1024 nt
	s_barrier
	s_cbranch_vccz .LBB0_471

; #define LAS __attribute__((address_space(3)))
; __device__ __forceinline__ unsigned pk2(float lo, float hi) { return pg8::cvt_pk_bf16_v(lo, hi); }
; __device__ __forceinline__ float bflo(unsigned w) { return __uint_as_float(w << 16); }
; __device__ __forceinline__ float bfhi(unsigned w) { return __uint_as_float(w & 0xffff0000u); }
; __device__ __forceinline__ float bf1(unsigned short b) { return __uint_as_float((unsigned)b << 16); }
; __device__ __forceinline__ v4u packf8(const float (&f)[8]) { v4u w; w.x = pk2(f[0], f[1]); w.y = pk2(f[2], f[3]); w.z = pk2(f[4], f[5]); w.w = pk2(f[6], f[7]); return w; }
; __device__ __forceinline__ void gdn_prep_all(const Params& P, LAS unsigned char* lds, int tid, int lane, int wave, int G) {
;     ...
;             for (int fr = 0; fr < 8; ++fr) {
;                 const int rho = fr >> 1, s2 = fr & 1, row = 16 * rho + i;
;                 v4u o; unsigned char* dst; int frp = fr;
;                 if (kind == 0) { const v2u lo = *(const LAS v2u*)(hb + XQK_OFF + row * 144 + (32 * s2 + 4 * q4) * 2), hi = *(const LAS v2u*)(hb + XQK_OFF + row * 144 + (32 * s2 + 16 + 4 * q4) * 2);
;                     o.x = lo.x; o.y = lo.y; o.z = hi.x; o.w = hi.y; dst = ops + OPS_QK;
;                     frp = (fr == 0) ? 0 : (fr == 2) ? 1 : (fr >= 4) ? fr - 2 : (fr == 1 ? 6 : 7); }
;                 else if (kind == 1) { const v2u lo = *(const LAS v2u*)(hb + QB_OFF + row * 144 + (32 * s2 + 4 * q4) * 2), hi = *(const LAS v2u*)(hb + QB_OFF + row * 144 + (32 * s2 + 16 + 4 * q4) * 2);
;                     const float e = sc[128 + row];
;                     o.x = pk2(bflo(lo.x) * e, bfhi(lo.x) * e); o.y = pk2(bflo(lo.y) * e, bfhi(lo.y) * e); o.z = pk2(bflo(hi.x) * e, bfhi(hi.x) * e); o.w = pk2(bflo(hi.y) * e, bfhi(hi.y) * e); dst = ops + OPS_QD; }
;                 else { float vv[8];
; #pragma unroll
;                     for (int e = 0; e < 8; ++e) { const int t = 32 * s2 + 16 * (e >> 2) + 4 * q4 + (e & 3); vv[e] = bf1(*(const LAS unsigned short*)(hb + KB_OFF + t * 144 + (16 * rho + i) * 2)) * sc[192 + t]; }
;                     o = packf8(vv); dst = ops + OPS_KT; }
;                 *(v4u*)(dst + (frp * 64 + lane) * 16) = o;
;             }
.LBB0_413:
	v_lshl_or_b32 v42, s51, 10, v113
	v_ashrrev_i32_e32 v43, 31, v42
	s_add_i32 s11, s11, 4
	v_lshl_add_u64 v[42:43], s[14:15], 0, v[42:43]
	v_add_u32_e32 v40, 32, v40
	v_add_u32_e32 v39, 64, v39
	v_add_u32_e32 v36, 0x80, v36
	v_add_u32_e32 v38, 64, v38
	s_cmp_lg_u32 s11, 8
	v_add_u32_e32 v37, 0x1200, v37
	s_waitcnt lgkmcnt(0)
	global_store_dwordx4 v[42:43], v[32:35], off nt
	s_cbranch_scc0 .LBB0_461

; #define LAS __attribute__((address_space(3)))
; __device__ __forceinline__ unsigned pk2(float lo, float hi) { return pg8::cvt_pk_bf16_v(lo, hi); }
; __device__ __forceinline__ float bflo(unsigned w) { return __uint_as_float(w << 16); }
; __device__ __forceinline__ float bfhi(unsigned w) { return __uint_as_float(w & 0xffff0000u); }
; __device__ __forceinline__ float bf1(unsigned short b) { return __uint_as_float((unsigned)b << 16); }
; __device__ __forceinline__ v4u packf8(const float (&f)[8]) { v4u w; w.x = pk2(f[0], f[1]); w.y = pk2(f[2], f[3]); w.z = pk2(f[4], f[5]); w.w = pk2(f[6], f[7]); return w; }
; __device__ __forceinline__ void gdn_prep_all(const Params& P, LAS unsigned char* lds, int tid, int lane, int wave, int G) {
;     ...
;                 if (kind == 0) { const v2u lo = *(const LAS v2u*)(hb + XQK_OFF + row * 144 + (32 * s2 + 4 * q4) * 2), hi = *(const LAS v2u*)(hb + XQK_OFF + row * 144 + (32 * s2 + 16 + 4 * q4) * 2);
;                     o.x = lo.x; o.y = lo.y; o.z = hi.x; o.w = hi.y; dst = ops + OPS_QK;
;                     frp = (fr == 0) ? 0 : (fr == 2) ? 1 : (fr >= 4) ? fr - 2 : (fr == 1 ? 6 : 7); }
;                 else if (kind == 1) { const v2u lo = *(const LAS v2u*)(hb + QB_OFF + row * 144 + (32 * s2 + 4 * q4) * 2), hi = *(const LAS v2u*)(hb + QB_OFF + row * 144 + (32 * s2 + 16 + 4 * q4) * 2);
;                     const float e = sc[128 + row];
;                     o.x = pk2(bflo(lo.x) * e, bfhi(lo.x) * e); o.y = pk2(bflo(lo.y) * e, bfhi(lo.y) * e); o.z = pk2(bflo(hi.x) * e, bfhi(hi.x) * e); o.w = pk2(bflo(hi.y) * e, bfhi(hi.y) * e); dst = ops + OPS_QD; }
;                 else { float vv[8];
; #pragma unroll
;                     for (int e = 0; e < 8; ++e) { const int t = 32 * s2 + 16 * (e >> 2) + 4 * q4 + (e & 3); vv[e] = bf1(*(const LAS unsigned short*)(hb + KB_OFF + t * 144 + (16 * rho + i) * 2)) * sc[192 + t]; }
;                     o = packf8(vv); dst = ops + OPS_KT; }
;                 *(v4u*)(dst + (frp * 64 + lane) * 16) = o;
;             }
.LBB0_424:
	v_lshl_or_b32 v44, s51, 10, v113
	v_ashrrev_i32_e32 v45, 31, v44
	v_lshl_add_u64 v[44:45], s[14:15], 0, v[44:45]
	s_mov_b64 vcc, -1
	s_mov_b64 s[58:59], 0
	s_cmp_lt_i32 s81, 2
	s_mov_b64 s[14:15], 0
	s_waitcnt lgkmcnt(0)
	global_store_dwordx4 v[44:45], v[32:35], off nt
	s_cbranch_scc1 .LBB0_430
	s_cmp_eq_u32 s81, 2
	s_mov_b64 s[14:15], -1
	s_cbranch_scc0 .LBB0_427
	v_mad_u32_u24 v32, v40, s5, v150
	ds_read2_b64 v[32:35], v32 offset0:8 offset1:12
	ds_read_b32 v44, v36
	s_mov_b64 s[14:15], 0
	s_waitcnt lgkmcnt(1)
	v_lshlrev_b32_e32 v46, 16, v32
	v_and_b32_e32 v47, 0xffff0000, v32
	s_waitcnt lgkmcnt(0)
	v_pk_mul_f32 v[46:47], v[44:45], v[46:47] op_sel_hi:[0,1]
	v_cvt_pk_bf16_f32 v32, v46, v47
	v_lshlrev_b32_e32 v46, 16, v33
	v_and_b32_e32 v47, 0xffff0000, v33
	v_pk_mul_f32 v[46:47], v[44:45], v[46:47] op_sel_hi:[0,1]
	v_cvt_pk_bf16_f32 v33, v46, v47
	v_lshlrev_b32_e32 v46, 16, v34
	v_and_b32_e32 v47, 0xffff0000, v34
	v_pk_mul_f32 v[46:47], v[44:45], v[46:47] op_sel_hi:[0,1]
	v_cvt_pk_bf16_f32 v34, v46, v47
	v_lshlrev_b32_e32 v46, 16, v35
	v_and_b32_e32 v47, 0xffff0000, v35
	v_pk_mul_f32 v[44:45], v[44:45], v[46:47] op_sel_hi:[0,1]
	v_cvt_pk_bf16_f32 v35, v44, v45

; #define LAS __attribute__((address_space(3)))
; __device__ __forceinline__ unsigned pk2(float lo, float hi) { return pg8::cvt_pk_bf16_v(lo, hi); }
; __device__ __forceinline__ float bflo(unsigned w) { return __uint_as_float(w << 16); }
; __device__ __forceinline__ float bfhi(unsigned w) { return __uint_as_float(w & 0xffff0000u); }
; __device__ __forceinline__ float bf1(unsigned short b) { return __uint_as_float((unsigned)b << 16); }
; __device__ __forceinline__ v4u packf8(const float (&f)[8]) { v4u w; w.x = pk2(f[0], f[1]); w.y = pk2(f[2], f[3]); w.z = pk2(f[4], f[5]); w.w = pk2(f[6], f[7]); return w; }
; __device__ __forceinline__ void gdn_prep_all(const Params& P, LAS unsigned char* lds, int tid, int lane, int wave, int G) {
;     ...
;                 if (kind == 0) { const v2u lo = *(const LAS v2u*)(hb + XQK_OFF + row * 144 + (32 * s2 + 4 * q4) * 2), hi = *(const LAS v2u*)(hb + XQK_OFF + row * 144 + (32 * s2 + 16 + 4 * q4) * 2);
;                     o.x = lo.x; o.y = lo.y; o.z = hi.x; o.w = hi.y; dst = ops + OPS_QK;
;                     frp = (fr == 0) ? 0 : (fr == 2) ? 1 : (fr >= 4) ? fr - 2 : (fr == 1 ? 6 : 7); }
;                 else if (kind == 1) { const v2u lo = *(const LAS v2u*)(hb + QB_OFF + row * 144 + (32 * s2 + 4 * q4) * 2), hi = *(const LAS v2u*)(hb + QB_OFF + row * 144 + (32 * s2 + 16 + 4 * q4) * 2);
;                     const float e = sc[128 + row];
;                     o.x = pk2(bflo(lo.x) * e, bfhi(lo.x) * e); o.y = pk2(bflo(lo.y) * e, bfhi(lo.y) * e); o.z = pk2(bflo(hi.x) * e, bfhi(hi.x) * e); o.w = pk2(bflo(hi.y) * e, bfhi(hi.y) * e); dst = ops + OPS_QD; }
;                 else { float vv[8];
; #pragma unroll
;                     for (int e = 0; e < 8; ++e) { const int t = 32 * s2 + 16 * (e >> 2) + 4 * q4 + (e & 3); vv[e] = bf1(*(const LAS unsigned short*)(hb + KB_OFF + t * 144 + (16 * rho + i) * 2)) * sc[192 + t]; }
;                     o = packf8(vv); dst = ops + OPS_KT; }
;                 *(v4u*)(dst + (frp * 64 + lane) * 16) = o;
;             }
.LBB0_434:
	v_lshl_or_b32 v44, v44, 10, v113
	v_ashrrev_i32_e32 v45, 31, v44
	v_lshl_add_u64 v[44:45], s[14:15], 0, v[44:45]
	s_mov_b64 vcc, -1
	s_mov_b64 s[58:59], 0
	s_cmp_lt_i32 s81, 2
	s_mov_b64 s[14:15], 0
	s_waitcnt lgkmcnt(0)
	global_store_dwordx4 v[44:45], v[32:35], off nt
	s_cbranch_scc1 .LBB0_441
	s_cmp_eq_u32 s81, 2
	s_mov_b64 s[14:15], -1
	s_cbranch_scc0 .LBB0_437
	v_add_u32_e32 v32, 0x800, v43
	ds_read2_b64 v[32:35], v32 offset0:32 offset1:36
	ds_read_b32 v44, v36 offset:64
	s_mov_b64 s[14:15], 0
	s_waitcnt lgkmcnt(1)
	v_lshlrev_b32_e32 v46, 16, v32
	v_and_b32_e32 v47, 0xffff0000, v32
	s_waitcnt lgkmcnt(0)
	v_pk_mul_f32 v[46:47], v[44:45], v[46:47] op_sel_hi:[0,1]
	v_cvt_pk_bf16_f32 v32, v46, v47
	v_lshlrev_b32_e32 v46, 16, v33
	v_and_b32_e32 v47, 0xffff0000, v33
	v_pk_mul_f32 v[46:47], v[44:45], v[46:47] op_sel_hi:[0,1]
	v_cvt_pk_bf16_f32 v33, v46, v47
	v_lshlrev_b32_e32 v46, 16, v34
	v_and_b32_e32 v47, 0xffff0000, v34
	v_pk_mul_f32 v[46:47], v[44:45], v[46:47] op_sel_hi:[0,1]
	v_cvt_pk_bf16_f32 v34, v46, v47
	v_lshlrev_b32_e32 v46, 16, v35
	v_and_b32_e32 v47, 0xffff0000, v35
	v_pk_mul_f32 v[44:45], v[44:45], v[46:47] op_sel_hi:[0,1]
	v_cvt_pk_bf16_f32 v35, v44, v45

; #define LAS __attribute__((address_space(3)))
; __device__ __forceinline__ unsigned pk2(float lo, float hi) { return pg8::cvt_pk_bf16_v(lo, hi); }
; __device__ __forceinline__ float bflo(unsigned w) { return __uint_as_float(w << 16); }
; __device__ __forceinline__ float bfhi(unsigned w) { return __uint_as_float(w & 0xffff0000u); }
; __device__ __forceinline__ float bf1(unsigned short b) { return __uint_as_float((unsigned)b << 16); }
; __device__ __forceinline__ v4u packf8(const float (&f)[8]) { v4u w; w.x = pk2(f[0], f[1]); w.y = pk2(f[2], f[3]); w.z = pk2(f[4], f[5]); w.w = pk2(f[6], f[7]); return w; }
; __device__ __forceinline__ void gdn_prep_all(const Params& P, LAS unsigned char* lds, int tid, int lane, int wave, int G) {
;     ...
;                 if (kind == 0) { const v2u lo = *(const LAS v2u*)(hb + XQK_OFF + row * 144 + (32 * s2 + 4 * q4) * 2), hi = *(const LAS v2u*)(hb + XQK_OFF + row * 144 + (32 * s2 + 16 + 4 * q4) * 2);
;                     o.x = lo.x; o.y = lo.y; o.z = hi.x; o.w = hi.y; dst = ops + OPS_QK;
;                     frp = (fr == 0) ? 0 : (fr == 2) ? 1 : (fr >= 4) ? fr - 2 : (fr == 1 ? 6 : 7); }
;                 else if (kind == 1) { const v2u lo = *(const LAS v2u*)(hb + QB_OFF + row * 144 + (32 * s2 + 4 * q4) * 2), hi = *(const LAS v2u*)(hb + QB_OFF + row * 144 + (32 * s2 + 16 + 4 * q4) * 2);
;                     const float e = sc[128 + row];
;                     o.x = pk2(bflo(lo.x) * e, bfhi(lo.x) * e); o.y = pk2(bflo(lo.y) * e, bfhi(lo.y) * e); o.z = pk2(bflo(hi.x) * e, bfhi(hi.x) * e); o.w = pk2(bflo(hi.y) * e, bfhi(hi.y) * e); dst = ops + OPS_QD; }
;                 else { float vv[8];
; #pragma unroll
;                     for (int e = 0; e < 8; ++e) { const int t = 32 * s2 + 16 * (e >> 2) + 4 * q4 + (e & 3); vv[e] = bf1(*(const LAS unsigned short*)(hb + KB_OFF + t * 144 + (16 * rho + i) * 2)) * sc[192 + t]; }
;                     o = packf8(vv); dst = ops + OPS_KT; }
;                 *(v4u*)(dst + (frp * 64 + lane) * 16) = o;
;             }
.LBB0_448:
	v_lshl_or_b32 v42, s58, 10, v113
	v_ashrrev_i32_e32 v43, 31, v42
	v_lshl_add_u64 v[42:43], s[14:15], 0, v[42:43]
	s_waitcnt lgkmcnt(0)
	global_store_dwordx4 v[42:43], v[32:35], off nt
	v_add_u32_e32 v42, 16, v40
	s_mov_b64 vcc, -1
	s_mov_b64 s[58:59], 0
	s_cmp_lt_i32 s81, 2
	s_mov_b64 s[14:15], 0
	s_cbranch_scc1 .LBB0_454
	s_cmp_eq_u32 s81, 2
	s_mov_b64 s[14:15], -1
	s_cbranch_scc0 .LBB0_451
	v_mad_u32_u24 v32, v42, s5, v150
	ds_read2_b64 v[32:35], v32 offset0:8 offset1:12
	ds_read_b32 v44, v36 offset:64
	s_mov_b64 s[14:15], 0
	s_waitcnt lgkmcnt(1)
	v_lshlrev_b32_e32 v46, 16, v32
	v_and_b32_e32 v47, 0xffff0000, v32
	s_waitcnt lgkmcnt(0)
	v_pk_mul_f32 v[46:47], v[44:45], v[46:47] op_sel_hi:[0,1]
	v_cvt_pk_bf16_f32 v32, v46, v47
	v_lshlrev_b32_e32 v46, 16, v33
	v_and_b32_e32 v47, 0xffff0000, v33
	v_pk_mul_f32 v[46:47], v[44:45], v[46:47] op_sel_hi:[0,1]
	v_cvt_pk_bf16_f32 v33, v46, v47
	v_lshlrev_b32_e32 v46, 16, v34
	v_and_b32_e32 v47, 0xffff0000, v34
	v_pk_mul_f32 v[46:47], v[44:45], v[46:47] op_sel_hi:[0,1]
	v_cvt_pk_bf16_f32 v34, v46, v47
	v_lshlrev_b32_e32 v46, 16, v35
	v_and_b32_e32 v47, 0xffff0000, v35
	v_pk_mul_f32 v[44:45], v[44:45], v[46:47] op_sel_hi:[0,1]
	v_cvt_pk_bf16_f32 v35, v44, v45

; __device__ __forceinline__ unsigned pk2(float lo, float hi) { return pg8::cvt_pk_bf16_v(lo, hi); }
; __device__ __forceinline__ void gdn_prep_all(const Params& P, LAS unsigned char* lds, int tid, int lane, int wave, int G) {
;     ...
;             if (wq < 2) {
; #pragma unroll
;                 for (int b = 0; b < 4; ++b)
; #pragma unroll
;                     for (int ct = 0; ct < 2; ++ct) { const int slice = 2 * (wq & 1) + ct; v2u o; o.x = pk2(X[b][ct][0], X[b][ct][1]); o.y = pk2(X[b][ct][2], X[b][ct][3]);
;                         *(v2u*)(ops + OPS_U + ((slice * 4 + b) * 64 + lane) * 8) = o; }
.LBB0_469:
	s_andn2_b64 vcc, exec, s[14:15]
	s_cbranch_vccnz .LBB0_346
	v_lshl_add_u64 v[32:33], s[16:17], 0, v[96:97]
	s_mov_b64 s[12:13], 0x8000
	v_lshl_add_u64 v[34:35], v[32:33], 0, s[12:13]
	v_add_co_u32_e32 v32, vcc, 0x8000, v32
	s_nop 1
	v_addc_co_u32_e32 v33, vcc, 0, v33, vcc
	global_store_dwordx2 v[32:33], v[40:41], off nt
	global_store_dwordx2 v[34:35], v[44:45], off offset:2048 nt
	global_store_dwordx2 v[34:35], v[42:43], off offset:512 nt
	global_store_dwordx2 v[34:35], v[46:47], off offset:2560 nt
	global_store_dwordx2 v[34:35], v[56:57], off offset:1024 nt
	global_store_dwordx2 v[34:35], v[58:59], off offset:3072 nt
	v_cvt_pk_bf16_f32 v32, v70, v71
	v_cvt_pk_bf16_f32 v33, v72, v73
	global_store_dwordx2 v[34:35], v[32:33], off offset:1536 nt
	v_cvt_pk_bf16_f32 v32, v74, v75
	v_cvt_pk_bf16_f32 v33, v76, v77
	global_store_dwordx2 v[34:35], v[32:33], off offset:3584 nt
	s_branch .LBB0_346
